# finalize: direction-1 fragment loads hoisted behind direction-0's (40 loads in flight under the Yl unpack and direction-0 MFMAs)
# baseline (speedup 1.0000x reference)
.LBB0_451:
	s_waitcnt vmcnt(0)
	v_mfma_f32_32x32x16_f16 v[50:65], v[216:219], v[200:203], v[50:65]
	v_readlane_b32 s3, v255, 3
	v_or_b32_e32 v163, 32, v151
	v_mfma_f32_32x32x16_f16 v[34:49], v[208:211], v[200:203], v[34:49]
	v_mfma_f32_32x32x16_f16 v[18:33], v[216:219], v[196:199], v[18:33]
	v_mfma_f32_32x32x16_f16 v[2:17], v[208:211], v[196:199], v[2:17]
	v_mfma_f32_32x32x16_f16 v[50:65], v[212:215], v[190:193], v[50:65]
	v_mfma_f32_32x32x16_f16 v[34:49], v[204:207], v[190:193], v[34:49]
	v_mfma_f32_32x32x16_f16 v[18:33], v[212:215], v[186:189], v[18:33]
	v_mfma_f32_32x32x16_f16 v[2:17], v[204:207], v[186:189], v[2:17]
	v_mfma_f32_32x32x16_f16 v[50:65], v[182:185], v[174:177], v[50:65]
	v_mfma_f32_32x32x16_f16 v[34:49], v[178:181], v[174:177], v[34:49]
	v_mfma_f32_32x32x16_f16 v[18:33], v[182:185], v[170:173], v[18:33]
	v_mfma_f32_32x32x16_f16 v[2:17], v[178:181], v[170:173], v[2:17]
	v_mfma_f32_32x32x16_f16 v[50:65], v[166:169], v[158:161], v[50:65]
	v_mfma_f32_32x32x16_f16 v[34:49], v[244:247], v[158:161], v[34:49]
	v_add_u32_e32 v70, s3, v150
	v_readlane_b32 s3, v255, 5
	v_ashrrev_i32_e32 v71, 31, v70
	v_lshl_add_u64 v[70:71], v[70:71], 4, s[66:67]
	global_load_dwordx4 v[70:73], v[70:71], off
	v_mfma_f32_32x32x16_f16 v[18:33], v[166:169], v[154:157], v[18:33]
	v_add_u32_e32 v78, s3, v150
	v_ashrrev_i32_e32 v79, 31, v78
	v_lshl_add_u64 v[78:79], v[78:79], 4, s[66:67]
	v_readlane_b32 s3, v255, 7
	global_load_dwordx4 v[130:133], v[78:79], off
	s_nop 0
	v_add_u32_e32 v78, s3, v150
	v_readlane_b32 s3, v255, 10
	v_mfma_f32_32x32x16_f16 v[2:17], v[244:247], v[154:157], v[2:17]
	v_add_u32_e32 v66, s79, v150
	v_add_u32_e32 v82, s3, v150
	v_mul_u32_u24_e32 v74, 0x110, v151
	v_ashrrev_i32_e32 v67, 31, v66
	v_ashrrev_i32_e32 v79, 31, v78
	v_ashrrev_i32_e32 v83, 31, v82
	v_lshl_add_u64 v[66:67], v[66:67], 4, s[66:67]
	v_add3_u32 v153, 0, v153, v74
	v_lshl_add_u64 v[78:79], v[78:79], 4, s[66:67]
	v_lshl_add_u64 v[82:83], v[82:83], 4, s[66:67]
	v_readlane_b32 s3, v255, 11
	global_load_dwordx4 v[66:69], v[66:67], off
	ds_read_b128 v[74:77], v153 offset:8704
	global_load_dwordx4 v[134:137], v[78:79], off
	ds_read_b128 v[78:81], v153
	ds_read_b128 v[138:141], v153 offset:32
	ds_read_b128 v[142:145], v153 offset:8736
	global_load_dwordx4 v[146:149], v[82:83], off
	v_add_u32_e32 v82, s3, v150
	v_ashrrev_i32_e32 v83, 31, v82
	v_lshl_add_u64 v[82:83], v[82:83], 4, s[66:67]
	v_readlane_b32 s3, v255, 12
	global_load_dwordx4 v[154:157], v[82:83], off
	ds_read_b128 v[158:161], v153 offset:64
	ds_read_b128 v[164:167], v153 offset:8768
	v_add_u32_e32 v82, s3, v150
	v_ashrrev_i32_e32 v83, 31, v82
	v_lshl_add_u64 v[82:83], v[82:83], 4, s[66:67]
	v_readlane_b32 s3, v255, 13
	global_load_dwordx4 v[168:171], v[82:83], off
	s_nop 0
	v_add_u32_e32 v82, s3, v150
	v_ashrrev_i32_e32 v83, 31, v82
	v_lshl_add_u64 v[82:83], v[82:83], 4, s[66:67]
	global_load_dwordx4 v[172:175], v[82:83], off
	ds_read_b128 v[176:179], v153 offset:96
	ds_read_b128 v[180:183], v153 offset:8800
	s_waitcnt vmcnt(5) lgkmcnt(6)
	v_mfma_f32_32x32x16_bf16 v[114:129], v[66:69], v[78:81], 0
	v_mfma_f32_32x32x16_bf16 v[98:113], v[70:73], v[78:81], 0
	v_mfma_f32_32x32x16_bf16 v[82:97], v[66:69], v[74:77], 0
	v_mfma_f32_32x32x16_bf16 v[66:81], v[70:73], v[74:77], 0
	s_waitcnt lgkmcnt(5)
	v_mfma_f32_32x32x16_bf16 v[114:129], v[130:133], v[138:141], v[114:129]
	s_waitcnt vmcnt(4)
	v_mfma_f32_32x32x16_bf16 v[98:113], v[134:137], v[138:141], v[98:113]
	s_waitcnt lgkmcnt(4)
	v_mfma_f32_32x32x16_bf16 v[82:97], v[130:133], v[142:145], v[82:97]
	v_mfma_f32_32x32x16_bf16 v[66:81], v[134:137], v[142:145], v[66:81]
	s_waitcnt vmcnt(3) lgkmcnt(3)
	v_mfma_f32_32x32x16_bf16 v[114:129], v[146:149], v[158:161], v[114:129]
	s_waitcnt vmcnt(2)
	v_mfma_f32_32x32x16_bf16 v[98:113], v[154:157], v[158:161], v[98:113]
	s_waitcnt lgkmcnt(2)
	v_mfma_f32_32x32x16_bf16 v[82:97], v[146:149], v[164:167], v[82:97]
	v_mfma_f32_32x32x16_bf16 v[66:81], v[154:157], v[164:167], v[66:81]
	s_waitcnt vmcnt(1) lgkmcnt(1)
	v_mfma_f32_32x32x16_bf16 v[114:129], v[168:171], v[176:179], v[114:129]
	s_waitcnt vmcnt(0)
	v_mfma_f32_32x32x16_bf16 v[98:113], v[172:175], v[176:179], v[98:113]
	s_waitcnt lgkmcnt(0)
	v_mfma_f32_32x32x16_bf16 v[82:97], v[168:171], v[180:183], v[82:97]
	v_mfma_f32_32x32x16_bf16 v[66:81], v[172:175], v[180:183], v[66:81]
	v_readlane_b32 s3, v255, 15
	v_add_u32_e32 v140, s82, v150
	v_add_u32_e32 v146, s83, v150
	v_add_u32_e32 v130, s3, v150
	v_readlane_b32 s3, v255, 17
	v_add_u32_e32 v148, s42, v150
	v_add_u32_e32 v158, s43, v150
	v_add_u32_e32 v132, s3, v150
	v_readlane_b32 s3, v255, 9
	v_add_u32_e32 v160, s85, v150
	v_ashrrev_i32_e32 v131, 31, v130
	v_add_u32_e32 v138, s3, v150
	v_ashrrev_i32_e32 v133, 31, v132
	v_ashrrev_i32_e32 v139, 31, v138
	v_ashrrev_i32_e32 v141, 31, v140
	v_ashrrev_i32_e32 v147, 31, v146
	v_ashrrev_i32_e32 v149, 31, v148
	v_ashrrev_i32_e32 v159, 31, v158
	v_ashrrev_i32_e32 v161, 31, v160
	v_lshl_add_u64 v[130:131], v[130:131], 4, s[66:67]
	v_lshl_add_u64 v[134:135], v[132:133], 4, s[66:67]
	v_lshl_add_u64 v[138:139], v[138:139], 4, s[66:67]
	v_lshl_add_u64 v[142:143], v[140:141], 4, s[66:67]
	v_lshl_add_u64 v[146:147], v[146:147], 4, s[66:67]
	v_lshl_add_u64 v[154:155], v[148:149], 4, s[66:67]
	v_lshl_add_u64 v[158:159], v[158:159], 4, s[66:67]
	v_lshl_add_u64 v[164:165], v[160:161], 4, s[66:67]
	global_load_dwordx4 v[130:133], v[130:131], off
	s_nop 0
	global_load_dwordx4 v[134:137], v[134:135], off
	s_nop 0
	global_load_dwordx4 v[138:141], v[138:139], off
	s_nop 0
	global_load_dwordx4 v[142:145], v[142:143], off
	s_nop 0
	global_load_dwordx4 v[146:149], v[146:147], off
	s_nop 0
	global_load_dwordx4 v[154:157], v[154:155], off
	s_nop 0
	global_load_dwordx4 v[158:161], v[158:159], off
	s_nop 0
	global_load_dwordx4 v[164:167], v[164:165], off
	ds_read_b128 v[168:171], v153 offset:128
	ds_read_b128 v[172:175], v153 offset:160
	ds_read_b128 v[176:179], v153 offset:8832
	ds_read_b128 v[180:183], v153 offset:8864
	ds_read_b128 v[184:187], v153 offset:192
	ds_read_b128 v[188:191], v153 offset:224
	ds_read_b128 v[196:199], v153 offset:8896
	ds_read_b128 v[200:203], v153 offset:8928
	s_waitcnt vmcnt(7) lgkmcnt(7)
	v_mfma_f32_32x32x16_bf16 v[114:129], v[130:133], v[168:171], v[114:129]
	s_waitcnt vmcnt(6)
	v_mfma_f32_32x32x16_bf16 v[98:113], v[134:137], v[168:171], v[98:113]
	s_waitcnt lgkmcnt(5)
	v_mfma_f32_32x32x16_bf16 v[82:97], v[130:133], v[176:179], v[82:97]
	v_mfma_f32_32x32x16_bf16 v[66:81], v[134:137], v[176:179], v[66:81]
	s_waitcnt vmcnt(5)
	v_mfma_f32_32x32x16_bf16 v[114:129], v[138:141], v[172:175], v[114:129]
	s_waitcnt vmcnt(4)
	v_mfma_f32_32x32x16_bf16 v[98:113], v[142:145], v[172:175], v[98:113]
	s_waitcnt lgkmcnt(4)
	v_mfma_f32_32x32x16_bf16 v[82:97], v[138:141], v[180:183], v[82:97]
	v_mfma_f32_32x32x16_bf16 v[66:81], v[142:145], v[180:183], v[66:81]
	s_waitcnt vmcnt(3) lgkmcnt(3)
	v_mfma_f32_32x32x16_bf16 v[114:129], v[146:149], v[184:187], v[114:129]
	s_waitcnt vmcnt(2)
	v_mfma_f32_32x32x16_bf16 v[98:113], v[154:157], v[184:187], v[98:113]
	s_waitcnt lgkmcnt(1)
	v_mfma_f32_32x32x16_bf16 v[82:97], v[146:149], v[196:199], v[82:97]
	v_mfma_f32_32x32x16_bf16 v[66:81], v[154:157], v[196:199], v[66:81]
	s_waitcnt vmcnt(1)
	v_mfma_f32_32x32x16_bf16 v[114:129], v[158:161], v[188:191], v[114:129]
	s_waitcnt vmcnt(0)
	v_mfma_f32_32x32x16_bf16 v[98:113], v[164:167], v[188:191], v[98:113]
	s_waitcnt lgkmcnt(0)
	v_mfma_f32_32x32x16_bf16 v[82:97], v[158:161], v[200:203], v[82:97]
	v_mfma_f32_32x32x16_bf16 v[66:81], v[164:167], v[200:203], v[66:81]
	s_or_b32 s0, s1, s0
	v_or_b32_e32 v154, s0, v151
	v_ashrrev_i32_e32 v155, 31, v154
	v_lshl_add_u64 v[130:131], v[154:155], 3, s[40:41]
	v_lshlrev_b64 v[130:131], 2, v[130:131]
	v_lshl_add_u64 v[132:133], s[60:61], 0, v[130:131]
	v_lshl_add_u64 v[130:131], s[62:63], 0, v[130:131]
	global_load_dword v162, v[132:133], off
	global_load_dword v164, v[130:131], off
	v_add_f32_e32 v132, 0, v50
	v_add_f32_e32 v132, v51, v132
	v_add_f32_e32 v132, v52, v132
	v_add_f32_e32 v132, v53, v132
	v_add_f32_e32 v148, v54, v132
	v_add_f32_e32 v148, v55, v148
	v_add_f32_e32 v148, v56, v148
	v_add_f32_e32 v148, v57, v148
	v_add_f32_e32 v148, v58, v148
	v_add_f32_e32 v148, v59, v148
	v_add_f32_e32 v148, v60, v148
	v_add_f32_e32 v148, v61, v148
	v_add_f32_e32 v148, v62, v148
	v_add_f32_e32 v148, v63, v148
	v_add_f32_e32 v148, v64, v148
	v_add_f32_e32 v148, v65, v148
	v_add_f32_e32 v148, v34, v148
	v_add_f32_e32 v148, v35, v148
	v_add_f32_e32 v148, v36, v148
	v_add_f32_e32 v148, v37, v148
	v_add_f32_e32 v148, v38, v148
	v_add_f32_e32 v148, v39, v148
	v_add_f32_e32 v148, v40, v148
	v_add_f32_e32 v148, v41, v148
	v_add_f32_e32 v148, v42, v148
	v_add_f32_e32 v148, v43, v148
	v_add_f32_e32 v148, v44, v148
	v_add_f32_e32 v148, v45, v148
	v_add_f32_e32 v148, v46, v148
	v_lshlrev_b32_e32 v130, 2, v152
	s_movk_i32 s3, 0x410
	v_add_f32_e32 v148, v47, v148
	v_lshlrev_b32_e32 v131, 2, v150
	v_mad_u32_u24 v186, v151, s3, 0
	v_add_lshl_u32 v165, v130, s84, 1
	v_add_f32_e32 v148, v48, v148
	v_xor_b32_e32 v155, 0x80, v131
	v_add_u32_e32 v187, v186, v165
	v_add_f32_e32 v148, v49, v148
	ds_read_b64 v[146:147], v187 offset:17408
	ds_bpermute_b32 v149, v155, v148
	v_ashrrev_i32_e32 v131, 31, v130
	v_lshlrev_b64 v[130:131], 2, v[130:131]
	v_lshl_add_u64 v[150:151], s[80:81], 0, v[130:131]
	s_waitcnt lgkmcnt(1)
	v_lshlrev_b32_e32 v190, 16, v146
	v_and_b32_e32 v191, 0xffff0000, v146
	s_waitcnt lgkmcnt(0)
	v_add_f32_e32 v146, v148, v149
	v_mul_f32_e32 v146, 0x3c800000, v146
	v_pk_add_f32 v[196:197], v[50:51], v[146:147] op_sel_hi:[1,0] neg_lo:[0,1] neg_hi:[0,1]
	v_pk_add_f32 v[192:193], v[52:53], v[146:147] op_sel_hi:[1,0] neg_lo:[0,1] neg_hi:[0,1]
	v_pk_add_f32 v[176:177], v[60:61], v[146:147] op_sel_hi:[1,0] neg_lo:[0,1] neg_hi:[0,1]
	v_pk_mul_f32 v[60:61], v[196:197], v[196:197]
	v_pk_add_f32 v[178:179], v[58:59], v[146:147] op_sel_hi:[1,0] neg_lo:[0,1] neg_hi:[0,1]
	v_pk_mul_f32 v[58:59], v[192:193], v[192:193]
	v_add_f32_e32 v60, v60, v61
	v_pk_add_f32 v[200:201], v[54:55], v[146:147] op_sel_hi:[1,0] neg_lo:[0,1] neg_hi:[0,1]
	v_add_f32_e32 v58, v58, v60
	v_pk_mul_f32 v[180:181], v[200:201], v[200:201]
	v_add_f32_e32 v58, v59, v58
	v_pk_add_f32 v[198:199], v[56:57], v[146:147] op_sel_hi:[1,0] neg_lo:[0,1] neg_hi:[0,1]
	v_add_f32_e32 v58, v180, v58
	v_pk_mul_f32 v[148:149], v[198:199], v[198:199]
	v_add_f32_e32 v58, v181, v58
	v_add_f32_e32 v58, v148, v58
	v_lshl_add_u64 v[152:153], s[96:97], 0, v[130:131]
	global_load_dwordx4 v[138:141], v[150:151], off
	global_load_dwordx4 v[130:133], v[150:151], off offset:32
	global_load_dwordx4 v[142:145], v[152:153], off
	global_load_dwordx4 v[134:137], v[152:153], off offset:32
	v_pk_mul_f32 v[204:205], v[178:179], v[178:179]
	v_add_f32_e32 v58, v149, v58
	v_add_f32_e32 v58, v204, v58
	v_pk_mul_f32 v[202:203], v[176:177], v[176:177]
	v_add_f32_e32 v58, v205, v58
	v_pk_add_f32 v[170:171], v[62:63], v[146:147] op_sel_hi:[1,0] neg_lo:[0,1] neg_hi:[0,1]
	v_add_f32_e32 v58, v202, v58
	v_pk_mul_f32 v[62:63], v[170:171], v[170:171]
	v_add_f32_e32 v58, v203, v58
	v_pk_add_f32 v[166:167], v[64:65], v[146:147] op_sel_hi:[1,0] neg_lo:[0,1] neg_hi:[0,1]
	v_add_f32_e32 v58, v62, v58
	v_pk_mul_f32 v[206:207], v[166:167], v[166:167]
	v_add_f32_e32 v58, v63, v58
	v_pk_add_f32 v[174:175], v[34:35], v[146:147] op_sel_hi:[1,0] neg_lo:[0,1] neg_hi:[0,1]
	v_add_f32_e32 v58, v206, v58
	v_pk_mul_f32 v[34:35], v[174:175], v[174:175]
	v_add_f32_e32 v58, v207, v58
	v_pk_add_f32 v[168:169], v[36:37], v[146:147] op_sel_hi:[1,0] neg_lo:[0,1] neg_hi:[0,1]
	v_add_f32_e32 v34, v34, v58
	v_pk_mul_f32 v[36:37], v[168:169], v[168:169]
	v_add_f32_e32 v34, v35, v34
	v_pk_add_f32 v[172:173], v[38:39], v[146:147] op_sel_hi:[1,0] neg_lo:[0,1] neg_hi:[0,1]
	v_add_f32_e32 v34, v36, v34
	v_pk_mul_f32 v[38:39], v[172:173], v[172:173]
	v_add_f32_e32 v34, v37, v34
	v_pk_add_f32 v[64:65], v[40:41], v[146:147] op_sel_hi:[1,0] neg_lo:[0,1] neg_hi:[0,1]
	v_add_f32_e32 v34, v38, v34
	v_pk_mul_f32 v[40:41], v[64:65], v[64:65]
	v_add_f32_e32 v34, v39, v34
	v_pk_add_f32 v[42:43], v[42:43], v[146:147] op_sel_hi:[1,0] neg_lo:[0,1] neg_hi:[0,1]
	v_add_f32_e32 v34, v40, v34
	v_lshlrev_b32_e32 v188, 16, v147
	v_and_b32_e32 v189, 0xffff0000, v147
	v_pk_add_f32 v[160:161], v[44:45], v[146:147] op_sel_hi:[1,0] neg_lo:[0,1] neg_hi:[0,1]
	v_pk_add_f32 v[158:159], v[46:47], v[146:147] op_sel_hi:[1,0] neg_lo:[0,1] neg_hi:[0,1]
	v_pk_add_f32 v[156:157], v[48:49], v[146:147] op_sel_hi:[1,0] neg_lo:[0,1] neg_hi:[0,1]
	v_pk_mul_f32 v[146:147], v[42:43], v[42:43]
	v_add_f32_e32 v34, v41, v34
	v_add_f32_e32 v34, v146, v34
	global_load_dwordx4 v[52:55], v[150:151], off offset:64
	global_load_dwordx4 v[44:47], v[150:151], off offset:96
	v_add_f32_e32 v34, v147, v34
	global_load_dwordx4 v[146:149], v[152:153], off offset:64
	global_load_dwordx4 v[60:63], v[152:153], off offset:96
	v_pk_mul_f32 v[48:49], v[160:161], v[160:161]
	v_pk_mul_f32 v[50:51], v[158:159], v[158:159]
	v_add_f32_e32 v34, v48, v34
	v_add_f32_e32 v34, v49, v34
	v_add_f32_e32 v34, v50, v34
	v_pk_mul_f32 v[56:57], v[156:157], v[156:157]
	v_add_f32_e32 v34, v51, v34
	v_add_f32_e32 v34, v56, v34
	v_add_f32_e32 v34, v57, v34
	ds_bpermute_b32 v35, v155, v34
	s_mov_b32 s1, 0xf800000
	s_waitcnt vmcnt(8)
	v_add_f32_e32 v162, v162, v164
	v_add_u32_e32 v182, 16, v165
	v_add_u32_e32 v208, v186, v182
	s_waitcnt lgkmcnt(0)
	v_add_f32_e32 v34, v34, v35
	v_fmamk_f32 v34, v34, 0x3c800000, v221
	v_mul_f32_e32 v35, 0x4f800000, v34
	v_cmp_gt_f32_e32 vcc, s1, v34
	v_add_u32_e32 v183, 32, v165
	v_add_u32_e32 v184, 48, v165
	v_cndmask_b32_e32 v48, v34, v35, vcc
	v_sqrt_f32_e32 v49, v48
	global_load_dwordx4 v[38:41], v[150:151], off offset:128
	global_load_dwordx4 v[34:37], v[150:151], off offset:160
	v_add_u32_e32 v209, v186, v183
	v_add_u32_e32 v180, 64, v165
	v_add_u32_e32 v50, -1, v49
	v_fma_f32 v51, -v50, v49, v48
	v_cmp_ge_f32_e64 s[36:37], 0, v51
	v_add_u32_e32 v51, 1, v49
	v_add_u32_e32 v210, v186, v184
	v_cndmask_b32_e64 v50, v49, v50, s[36:37]
	v_fma_f32 v49, -v51, v49, v48
	v_cmp_lt_f32_e64 s[36:37], 0, v49
	v_add_u32_e32 v202, v186, v180
	v_add_u32_e32 v181, 0x50, v165
	v_cndmask_b32_e64 v49, v50, v51, s[36:37]
	v_mul_f32_e32 v50, 0x37800000, v49
	v_cndmask_b32_e32 v49, v49, v50, vcc
	v_cmp_class_f32_e32 vcc, v48, v222
	v_add_u32_e32 v203, v186, v181
	v_add_u32_e32 v185, 0x60, v165
	v_cndmask_b32_e32 v164, v49, v48, vcc
	global_load_dwordx4 v[56:59], v[152:153], off offset:128
	global_load_dwordx4 v[48:51], v[152:153], off offset:160
	v_div_scale_f32 v204, s[28:29], v164, v164, 1.0
	v_rcp_f32_e32 v205, v204
	v_add_u32_e32 v206, v186, v185
	s_add_i32 s78, s78, s87
	s_add_i32 s91, s91, s87
	v_fma_f32 v207, -v204, v205, 1.0
	v_fmac_f32_e32 v205, v207, v205
	v_div_scale_f32 v207, vcc, 1.0, v164, 1.0
	v_mul_f32_e32 v211, v207, v205
	v_fma_f32 v212, -v204, v211, v207
	v_fmac_f32_e32 v211, v212, v205
	v_fma_f32 v204, -v204, v211, v207
	v_div_fmas_f32 v204, v204, v205, v211
	v_div_fixup_f32 v164, v204, v164, 1.0
	v_pk_mul_f32 v[196:197], v[196:197], v[164:165] op_sel_hi:[1,0]
	v_pk_mul_f32 v[178:179], v[178:179], v[164:165] op_sel_hi:[1,0]
	s_waitcnt vmcnt(9)
	v_pk_fma_f32 v[196:197], v[138:139], v[196:197], v[142:143]
	v_pk_mul_f32 v[170:171], v[170:171], v[164:165] op_sel_hi:[1,0]
	v_pk_fma_f32 v[190:191], v[162:163], v[190:191], v[196:197] op_sel_hi:[0,1,1]
	v_pk_mul_f32 v[114:115], v[114:115], v[190:191]
	v_pk_mul_f32 v[190:191], v[192:193], v[164:165] op_sel_hi:[1,0]
	v_cvt_pk_bf16_f32 v114, v114, v115
	v_pk_fma_f32 v[190:191], v[140:141], v[190:191], v[144:145]
	v_pk_mul_f32 v[196:197], v[200:201], v[164:165] op_sel_hi:[1,0]
	v_pk_fma_f32 v[188:189], v[162:163], v[188:189], v[190:191] op_sel_hi:[0,1,1]
	v_pk_mul_f32 v[116:117], v[116:117], v[188:189]
	s_waitcnt vmcnt(8)
	v_pk_fma_f32 v[196:197], v[130:131], v[196:197], v[134:135]
	v_cvt_pk_bf16_f32 v115, v116, v117
	ds_read_b64 v[116:117], v208 offset:17408
	ds_write_b64 v187, v[114:115] offset:17408
	ds_read_b64 v[188:189], v209 offset:17408
	ds_read_b64 v[190:191], v210 offset:17408
	ds_read_b64 v[192:193], v202 offset:17408
	v_pk_mul_f32 v[166:167], v[166:167], v[164:165] op_sel_hi:[1,0]
	v_pk_mul_f32 v[64:65], v[64:65], v[164:165] op_sel_hi:[1,0]
	s_waitcnt lgkmcnt(4)
	v_lshlrev_b32_e32 v114, 16, v116
	v_and_b32_e32 v115, 0xffff0000, v116
	v_pk_fma_f32 v[114:115], v[162:163], v[114:115], v[196:197] op_sel_hi:[0,1,1]
	v_pk_mul_f32 v[114:115], v[118:119], v[114:115]
	v_pk_mul_f32 v[118:119], v[198:199], v[164:165] op_sel_hi:[1,0]
	v_lshlrev_b32_e32 v116, 16, v117
	v_and_b32_e32 v117, 0xffff0000, v117
	v_pk_fma_f32 v[118:119], v[132:133], v[118:119], v[136:137]
	v_cvt_pk_bf16_f32 v196, v114, v115
	v_pk_fma_f32 v[116:117], v[162:163], v[116:117], v[118:119] op_sel_hi:[0,1,1]
	v_pk_mul_f32 v[116:117], v[120:121], v[116:117]
	s_waitcnt vmcnt(5)
	v_pk_fma_f32 v[178:179], v[52:53], v[178:179], v[146:147]
	v_cvt_pk_bf16_f32 v197, v116, v117
	global_load_dwordx4 v[114:117], v[150:151], off offset:192
	global_load_dwordx4 v[118:121], v[152:153], off offset:192
	ds_write_b64 v208, v[196:197] offset:17408
	s_waitcnt lgkmcnt(3)
	v_lshlrev_b32_e32 v196, 16, v188
	v_and_b32_e32 v197, 0xffff0000, v188
	v_pk_fma_f32 v[178:179], v[162:163], v[196:197], v[178:179] op_sel_hi:[0,1,1]
	v_pk_mul_f32 v[178:179], v[122:123], v[178:179]
	v_pk_mul_f32 v[122:123], v[176:177], v[164:165] op_sel_hi:[1,0]
	v_lshlrev_b32_e32 v188, 16, v189
	v_and_b32_e32 v189, 0xffff0000, v189
	v_pk_fma_f32 v[122:123], v[54:55], v[122:123], v[148:149]
	v_cvt_pk_bf16_f32 v178, v178, v179
	v_pk_fma_f32 v[122:123], v[162:163], v[188:189], v[122:123] op_sel_hi:[0,1,1]
	v_pk_mul_f32 v[176:177], v[124:125], v[122:123]
	global_load_dwordx4 v[122:125], v[150:151], off offset:224
	s_nop 0
	global_load_dwordx4 v[150:153], v[152:153], off offset:224
	v_cvt_pk_bf16_f32 v179, v176, v177
	ds_write_b64 v209, v[178:179] offset:17408
	s_waitcnt lgkmcnt(3)
	v_lshlrev_b32_e32 v176, 16, v190
	v_and_b32_e32 v177, 0xffff0000, v190
	v_lshlrev_b32_e32 v178, 16, v191
	v_and_b32_e32 v179, 0xffff0000, v191
	s_waitcnt vmcnt(8)
	v_pk_fma_f32 v[170:171], v[44:45], v[170:171], v[60:61]
	v_pk_fma_f32 v[166:167], v[46:47], v[166:167], v[62:63]
	v_pk_fma_f32 v[170:171], v[162:163], v[176:177], v[170:171] op_sel_hi:[0,1,1]
	v_pk_fma_f32 v[166:167], v[162:163], v[178:179], v[166:167] op_sel_hi:[0,1,1]
	v_pk_mul_f32 v[126:127], v[126:127], v[170:171]
	v_pk_mul_f32 v[128:129], v[128:129], v[166:167]
	v_cvt_pk_bf16_f32 v126, v126, v127
	v_cvt_pk_bf16_f32 v127, v128, v129
	v_pk_mul_f32 v[166:167], v[174:175], v[164:165] op_sel_hi:[1,0]
	ds_write_b64 v210, v[126:127] offset:17408
	s_waitcnt lgkmcnt(3)
	v_lshlrev_b32_e32 v126, 16, v192
	v_and_b32_e32 v127, 0xffff0000, v192
	s_waitcnt vmcnt(5)
	v_pk_fma_f32 v[166:167], v[38:39], v[166:167], v[56:57]
	v_lshlrev_b32_e32 v128, 16, v193
	v_pk_fma_f32 v[126:127], v[162:163], v[126:127], v[166:167] op_sel_hi:[0,1,1]
	v_pk_mul_f32 v[98:99], v[98:99], v[126:127]
	v_pk_mul_f32 v[126:127], v[168:169], v[164:165] op_sel_hi:[1,0]
	v_and_b32_e32 v129, 0xffff0000, v193
	v_pk_fma_f32 v[126:127], v[40:41], v[126:127], v[58:59]
	v_cvt_pk_bf16_f32 v98, v98, v99
	v_pk_fma_f32 v[126:127], v[162:163], v[128:129], v[126:127] op_sel_hi:[0,1,1]
	v_pk_mul_f32 v[100:101], v[100:101], v[126:127]
	v_pk_mul_f32 v[168:169], v[172:173], v[164:165] op_sel_hi:[1,0]
	v_cvt_pk_bf16_f32 v99, v100, v101
	ds_read_b64 v[100:101], v203 offset:17408
	s_waitcnt vmcnt(4)
	v_pk_fma_f32 v[168:169], v[34:35], v[168:169], v[48:49]
	ds_write_b64 v202, v[98:99] offset:17408
	v_add_u32_e32 v98, 0x70, v165
	v_add_u32_e32 v99, v186, v98
	s_waitcnt lgkmcnt(1)
	v_lshlrev_b32_e32 v166, 16, v100
	v_and_b32_e32 v167, 0xffff0000, v100
	v_pk_fma_f32 v[166:167], v[162:163], v[166:167], v[168:169] op_sel_hi:[0,1,1]
	v_or_b32_e32 v168, 32, v154
	v_ashrrev_i32_e32 v169, 31, v168
	v_lshl_add_u64 v[168:169], v[168:169], 3, s[40:41]
	v_lshlrev_b64 v[168:169], 2, v[168:169]
	v_lshl_add_u64 v[170:171], s[60:61], 0, v[168:169]
	v_lshl_add_u64 v[168:169], s[62:63], 0, v[168:169]
	ds_read_b64 v[126:127], v206 offset:17408
	ds_read_b64 v[128:129], v99 offset:17408
	global_load_dword v154, v[170:171], off
	s_nop 0
	global_load_dword v168, v[168:169], off
	v_lshlrev_b32_e32 v100, 16, v101
	v_and_b32_e32 v101, 0xffff0000, v101
	v_pk_fma_f32 v[64:65], v[36:37], v[64:65], v[50:51]
	v_pk_mul_f32 v[102:103], v[102:103], v[166:167]
	v_pk_fma_f32 v[64:65], v[162:163], v[100:101], v[64:65] op_sel_hi:[0,1,1]
	v_pk_mul_f32 v[64:65], v[104:105], v[64:65]
	v_cvt_pk_bf16_f32 v100, v102, v103
	v_cvt_pk_bf16_f32 v101, v64, v65
	v_pk_mul_f32 v[42:43], v[42:43], v[164:165] op_sel_hi:[1,0]
	ds_write_b64 v203, v[100:101] offset:17408
	s_waitcnt lgkmcnt(2)
	v_lshlrev_b32_e32 v64, 16, v126
	v_and_b32_e32 v65, 0xffff0000, v126
	v_pk_mul_f32 v[100:101], v[160:161], v[164:165] op_sel_hi:[1,0]
	s_cmpk_gt_i32 s78, 0xff
	s_waitcnt vmcnt(4)
	v_pk_fma_f32 v[42:43], v[114:115], v[42:43], v[118:119]
	s_nop 0
	v_pk_fma_f32 v[42:43], v[162:163], v[64:65], v[42:43] op_sel_hi:[0,1,1]
	v_lshlrev_b32_e32 v64, 16, v127
	v_and_b32_e32 v65, 0xffff0000, v127
	v_pk_fma_f32 v[100:101], v[116:117], v[100:101], v[120:121]
	v_pk_mul_f32 v[42:43], v[106:107], v[42:43]
	v_pk_fma_f32 v[64:65], v[162:163], v[64:65], v[100:101] op_sel_hi:[0,1,1]
	v_pk_mul_f32 v[64:65], v[108:109], v[64:65]
	v_cvt_pk_bf16_f32 v42, v42, v43
	v_cvt_pk_bf16_f32 v43, v64, v65
	v_pk_mul_f32 v[64:65], v[158:159], v[164:165] op_sel_hi:[1,0]
	ds_write_b64 v206, v[42:43] offset:17408
	s_waitcnt lgkmcnt(2)
	v_lshlrev_b32_e32 v42, 16, v128
	v_and_b32_e32 v43, 0xffff0000, v128
	s_waitcnt vmcnt(2)
	v_pk_fma_f32 v[64:65], v[122:123], v[64:65], v[150:151]
	v_pk_mul_f32 v[100:101], v[156:157], v[164:165] op_sel_hi:[1,0]
	v_pk_fma_f32 v[42:43], v[162:163], v[42:43], v[64:65] op_sel_hi:[0,1,1]
	v_lshlrev_b32_e32 v64, 16, v129
	v_and_b32_e32 v65, 0xffff0000, v129
	v_pk_fma_f32 v[100:101], v[124:125], v[100:101], v[152:153]
	v_pk_mul_f32 v[42:43], v[110:111], v[42:43]
	v_pk_fma_f32 v[64:65], v[162:163], v[64:65], v[100:101] op_sel_hi:[0,1,1]
	v_add_f32_e32 v100, 0, v18
	v_add_f32_e32 v100, v19, v100
	v_add_f32_e32 v100, v20, v100
	v_add_f32_e32 v100, v21, v100
	v_add_f32_e32 v100, v22, v100
	v_add_f32_e32 v100, v23, v100
	v_add_f32_e32 v100, v24, v100
	v_add_f32_e32 v100, v25, v100
	v_add_f32_e32 v100, v26, v100
	v_add_f32_e32 v100, v27, v100
	v_add_f32_e32 v100, v28, v100
	v_add_f32_e32 v100, v29, v100
	v_add_f32_e32 v100, v30, v100
	v_add_f32_e32 v100, v31, v100
	v_add_f32_e32 v100, v32, v100
	v_add_f32_e32 v100, v33, v100
	v_add_f32_e32 v100, v2, v100
	v_add_f32_e32 v100, v3, v100
	v_add_f32_e32 v100, v4, v100
	v_add_f32_e32 v100, v5, v100
	v_add_f32_e32 v100, v6, v100
	v_add_f32_e32 v100, v7, v100
	v_add_f32_e32 v100, v8, v100
	v_add_f32_e32 v100, v9, v100
	v_add_f32_e32 v100, v10, v100
	v_add_f32_e32 v100, v11, v100
	v_add_f32_e32 v100, v12, v100
	v_add_f32_e32 v100, v13, v100
	v_add_f32_e32 v100, v14, v100
	v_add_f32_e32 v100, v15, v100
	v_add_f32_e32 v100, v16, v100
	v_add_f32_e32 v100, v17, v100
	ds_bpermute_b32 v101, v155, v100
	v_pk_mul_f32 v[64:65], v[112:113], v[64:65]
	v_cvt_pk_bf16_f32 v42, v42, v43
	v_cvt_pk_bf16_f32 v43, v64, v65
	ds_write_b64 v99, v[42:43] offset:17408
	s_waitcnt lgkmcnt(1)
	v_add_f32_e32 v42, v100, v101
	v_mul_f32_e32 v100, 0x3c800000, v42
	v_pk_add_f32 v[112:113], v[18:19], v[100:101] op_sel_hi:[1,0] neg_lo:[0,1] neg_hi:[0,1]
	v_pk_add_f32 v[20:21], v[20:21], v[100:101] op_sel_hi:[1,0] neg_lo:[0,1] neg_hi:[0,1]
	v_pk_mul_f32 v[126:127], v[112:113], v[112:113]
	v_pk_add_f32 v[64:65], v[12:13], v[100:101] op_sel_hi:[1,0] neg_lo:[0,1] neg_hi:[0,1]
	v_pk_add_f32 v[42:43], v[14:15], v[100:101] op_sel_hi:[1,0] neg_lo:[0,1] neg_hi:[0,1]
	v_pk_add_f32 v[12:13], v[16:17], v[100:101] op_sel_hi:[1,0] neg_lo:[0,1] neg_hi:[0,1]
	v_pk_mul_f32 v[110:111], v[20:21], v[20:21]
	v_pk_add_f32 v[24:25], v[24:25], v[100:101] op_sel_hi:[1,0] neg_lo:[0,1] neg_hi:[0,1]
	v_pk_add_f32 v[22:23], v[22:23], v[100:101] op_sel_hi:[1,0] neg_lo:[0,1] neg_hi:[0,1]
	v_pk_add_f32 v[28:29], v[28:29], v[100:101] op_sel_hi:[1,0] neg_lo:[0,1] neg_hi:[0,1]
	v_pk_add_f32 v[26:27], v[26:27], v[100:101] op_sel_hi:[1,0] neg_lo:[0,1] neg_hi:[0,1]
	v_pk_add_f32 v[32:33], v[32:33], v[100:101] op_sel_hi:[1,0] neg_lo:[0,1] neg_hi:[0,1]
	v_pk_add_f32 v[30:31], v[30:31], v[100:101] op_sel_hi:[1,0] neg_lo:[0,1] neg_hi:[0,1]
	v_pk_add_f32 v[16:17], v[4:5], v[100:101] op_sel_hi:[1,0] neg_lo:[0,1] neg_hi:[0,1]
	v_pk_add_f32 v[18:19], v[2:3], v[100:101] op_sel_hi:[1,0] neg_lo:[0,1] neg_hi:[0,1]
	v_pk_add_f32 v[2:3], v[8:9], v[100:101] op_sel_hi:[1,0] neg_lo:[0,1] neg_hi:[0,1]
	v_pk_add_f32 v[6:7], v[6:7], v[100:101] op_sel_hi:[1,0] neg_lo:[0,1] neg_hi:[0,1]
	v_pk_add_f32 v[4:5], v[10:11], v[100:101] op_sel_hi:[1,0] neg_lo:[0,1] neg_hi:[0,1]
	v_add_f32_e32 v100, v126, v127
	v_add_f32_e32 v100, v110, v100
	v_pk_mul_f32 v[156:157], v[22:23], v[22:23]
	v_add_f32_e32 v100, v111, v100
	v_add_f32_e32 v100, v156, v100
	v_pk_mul_f32 v[128:129], v[24:25], v[24:25]
	v_add_f32_e32 v100, v157, v100
	v_add_f32_e32 v100, v128, v100
	v_pk_mul_f32 v[160:161], v[26:27], v[26:27]
	v_add_f32_e32 v100, v129, v100
	v_add_f32_e32 v100, v160, v100
	v_pk_mul_f32 v[158:159], v[28:29], v[28:29]
	v_add_f32_e32 v100, v161, v100
	v_mad_u32_u24 v15, v163, s3, 0
	v_add_f32_e32 v100, v158, v100
	v_add_u32_e32 v99, v15, v165
	v_pk_mul_f32 v[164:165], v[30:31], v[30:31]
	v_add_f32_e32 v100, v159, v100
	v_add_f32_e32 v100, v164, v100
	v_pk_mul_f32 v[162:163], v[32:33], v[32:33]
	v_add_f32_e32 v100, v165, v100
	v_add_f32_e32 v100, v162, v100
	s_waitcnt vmcnt(0)
	v_add_f32_e32 v14, v154, v168
	v_pk_mul_f32 v[168:169], v[18:19], v[18:19]
	v_add_f32_e32 v100, v163, v100
	v_add_f32_e32 v100, v168, v100
	v_pk_mul_f32 v[166:167], v[16:17], v[16:17]
	v_add_f32_e32 v100, v169, v100
	v_add_f32_e32 v100, v166, v100
	v_pk_mul_f32 v[170:171], v[6:7], v[6:7]
	v_add_f32_e32 v100, v167, v100
	v_add_f32_e32 v100, v170, v100
	v_pk_mul_f32 v[8:9], v[2:3], v[2:3]
	v_add_f32_e32 v100, v171, v100
	v_add_f32_e32 v8, v8, v100
	v_pk_mul_f32 v[10:11], v[4:5], v[4:5]
	v_add_f32_e32 v8, v9, v8
	v_add_f32_e32 v8, v10, v8
	v_pk_mul_f32 v[102:103], v[64:65], v[64:65]
	v_add_f32_e32 v8, v11, v8
	v_add_f32_e32 v8, v102, v8
	v_pk_mul_f32 v[104:105], v[42:43], v[42:43]
	v_add_f32_e32 v8, v103, v8
	v_add_f32_e32 v8, v104, v8
	v_pk_mul_f32 v[106:107], v[12:13], v[12:13]
	v_add_f32_e32 v8, v105, v8
	v_add_f32_e32 v8, v106, v8
	v_add_f32_e32 v103, v107, v8
	ds_bpermute_b32 v104, v155, v103
	ds_read_b64 v[108:109], v99 offset:17408
	v_add_u32_e32 v154, v15, v182
	v_add_u32_e32 v172, v15, v183
	v_add_u32_e32 v173, v15, v184
	s_waitcnt lgkmcnt(1)
	v_add_f32_e32 v103, v103, v104
	v_fmamk_f32 v103, v103, 0x3c800000, v221
	v_mul_f32_e32 v104, 0x4f800000, v103
	v_cmp_gt_f32_e32 vcc, s1, v103
	s_waitcnt lgkmcnt(0)
	v_and_b32_e32 v105, 0xffff0000, v108
	v_lshlrev_b32_e32 v102, 16, v109
	v_cndmask_b32_e32 v106, v103, v104, vcc
	v_sqrt_f32_e32 v107, v106
	v_lshlrev_b32_e32 v104, 16, v108
	v_and_b32_e32 v103, 0xffff0000, v109
	ds_read_b64 v[8:9], v154 offset:17408
	ds_read_b64 v[10:11], v172 offset:17408
	ds_read_b64 v[100:101], v173 offset:17408
	v_add_u32_e32 v108, -1, v107
	v_fma_f32 v109, -v108, v107, v106
	v_cmp_ge_f32_e64 s[36:37], 0, v109
	v_add_u32_e32 v109, 1, v107
	v_add_u32_e32 v110, v15, v180
	v_cndmask_b32_e64 v108, v107, v108, s[36:37]
	v_fma_f32 v107, -v109, v107, v106
	v_cmp_lt_f32_e64 s[36:37], 0, v107
	v_add_u32_e32 v111, v15, v181
	v_add_u32_e32 v126, v15, v185
	v_cndmask_b32_e64 v107, v108, v109, s[36:37]
	v_mul_f32_e32 v108, 0x37800000, v107
	v_cndmask_b32_e32 v107, v107, v108, vcc
	v_cmp_class_f32_e32 vcc, v106, v222
	s_nop 1
	v_cndmask_b32_e32 v106, v107, v106, vcc
	v_div_scale_f32 v107, s[28:29], v106, v106, 1.0
	v_rcp_f32_e32 v108, v107
	s_nop 0
	v_fma_f32 v109, -v107, v108, 1.0
	v_fmac_f32_e32 v108, v109, v108
	v_div_scale_f32 v109, vcc, 1.0, v106, 1.0
	v_mul_f32_e32 v127, v109, v108
	v_fma_f32 v128, -v107, v127, v109
	v_fmac_f32_e32 v127, v128, v108
	v_fma_f32 v107, -v107, v127, v109
	v_div_fmas_f32 v107, v107, v108, v127
	v_div_fixup_f32 v106, v107, v106, 1.0
	v_pk_mul_f32 v[108:109], v[112:113], v[106:107] op_sel_hi:[1,0]
	v_pk_mul_f32 v[20:21], v[20:21], v[106:107] op_sel_hi:[1,0]
	v_pk_fma_f32 v[108:109], v[138:139], v[108:109], v[142:143]
	v_pk_fma_f32 v[20:21], v[140:141], v[20:21], v[144:145]
	v_pk_fma_f32 v[104:105], v[14:15], v[104:105], v[108:109] op_sel_hi:[0,1,1]
	v_pk_fma_f32 v[20:21], v[14:15], v[102:103], v[20:21] op_sel_hi:[0,1,1]
	v_pk_mul_f32 v[82:83], v[82:83], v[104:105]
	v_pk_mul_f32 v[20:21], v[84:85], v[20:21]
	v_pk_mul_f32 v[22:23], v[22:23], v[106:107] op_sel_hi:[1,0]
	v_cvt_pk_bf16_f32 v82, v82, v83
	v_cvt_pk_bf16_f32 v83, v20, v21
	s_waitcnt lgkmcnt(2)
	v_lshlrev_b32_e32 v20, 16, v8
	v_and_b32_e32 v21, 0xffff0000, v8
	v_pk_fma_f32 v[22:23], v[130:131], v[22:23], v[134:135]
	v_lshlrev_b32_e32 v8, 16, v9
	v_pk_fma_f32 v[20:21], v[14:15], v[20:21], v[22:23] op_sel_hi:[0,1,1]
	v_pk_mul_f32 v[22:23], v[24:25], v[106:107] op_sel_hi:[1,0]
	v_and_b32_e32 v9, 0xffff0000, v9
	v_pk_fma_f32 v[22:23], v[132:133], v[22:23], v[136:137]
	v_pk_mul_f32 v[20:21], v[86:87], v[20:21]
	v_pk_fma_f32 v[8:9], v[14:15], v[8:9], v[22:23] op_sel_hi:[0,1,1]
	v_pk_mul_f32 v[8:9], v[88:89], v[8:9]
	v_cvt_pk_bf16_f32 v20, v20, v21
	v_cvt_pk_bf16_f32 v21, v8, v9
	ds_write_b64 v154, v[20:21] offset:17408
	v_pk_mul_f32 v[20:21], v[26:27], v[106:107] op_sel_hi:[1,0]
	s_waitcnt lgkmcnt(2)
	v_lshlrev_b32_e32 v8, 16, v10
	v_and_b32_e32 v9, 0xffff0000, v10
	v_pk_fma_f32 v[20:21], v[52:53], v[20:21], v[146:147]
	v_lshlrev_b32_e32 v10, 16, v11
	v_pk_fma_f32 v[8:9], v[14:15], v[8:9], v[20:21] op_sel_hi:[0,1,1]
	v_pk_mul_f32 v[20:21], v[28:29], v[106:107] op_sel_hi:[1,0]
	v_and_b32_e32 v11, 0xffff0000, v11
	v_pk_fma_f32 v[20:21], v[54:55], v[20:21], v[148:149]
	v_pk_mul_f32 v[8:9], v[90:91], v[8:9]
	v_pk_fma_f32 v[10:11], v[14:15], v[10:11], v[20:21] op_sel_hi:[0,1,1]
	v_pk_mul_f32 v[10:11], v[92:93], v[10:11]
	v_cvt_pk_bf16_f32 v8, v8, v9
	v_cvt_pk_bf16_f32 v9, v10, v11
	v_pk_mul_f32 v[20:21], v[30:31], v[106:107] op_sel_hi:[1,0]
	ds_write_b64 v172, v[8:9] offset:17408
	s_waitcnt lgkmcnt(2)
	v_lshlrev_b32_e32 v8, 16, v100
	v_and_b32_e32 v9, 0xffff0000, v100
	v_pk_fma_f32 v[20:21], v[44:45], v[20:21], v[60:61]
	v_lshlrev_b32_e32 v10, 16, v101
	v_pk_fma_f32 v[8:9], v[14:15], v[8:9], v[20:21] op_sel_hi:[0,1,1]
	v_pk_mul_f32 v[20:21], v[32:33], v[106:107] op_sel_hi:[1,0]
	v_and_b32_e32 v11, 0xffff0000, v101
	v_pk_fma_f32 v[20:21], v[46:47], v[20:21], v[62:63]
	v_pk_mul_f32 v[8:9], v[94:95], v[8:9]
	v_pk_fma_f32 v[10:11], v[14:15], v[10:11], v[20:21] op_sel_hi:[0,1,1]
	v_pk_mul_f32 v[10:11], v[96:97], v[10:11]
	v_cvt_pk_bf16_f32 v8, v8, v9
	v_cvt_pk_bf16_f32 v9, v10, v11
	ds_write_b64 v173, v[8:9] offset:17408
	ds_read_b64 v[8:9], v110 offset:17408
	ds_write_b64 v99, v[82:83] offset:17408
	v_pk_mul_f32 v[16:17], v[16:17], v[106:107] op_sel_hi:[1,0]
	v_add_u32_e32 v15, v15, v98
	ds_read_b64 v[10:11], v111 offset:17408
	ds_read_b64 v[20:21], v126 offset:17408
	ds_read_b64 v[22:23], v15 offset:17408
	s_waitcnt lgkmcnt(4)
	v_lshlrev_b32_e32 v24, 16, v8
	v_and_b32_e32 v25, 0xffff0000, v8
	v_lshlrev_b32_e32 v8, 16, v9
	v_and_b32_e32 v9, 0xffff0000, v9
	v_pk_fma_f32 v[16:17], v[40:41], v[16:17], v[58:59]
	v_pk_mul_f32 v[6:7], v[6:7], v[106:107] op_sel_hi:[1,0]
	v_pk_fma_f32 v[8:9], v[14:15], v[8:9], v[16:17] op_sel_hi:[0,1,1]
	v_pk_mul_f32 v[8:9], v[68:69], v[8:9]
	v_pk_mul_f32 v[2:3], v[2:3], v[106:107] op_sel_hi:[1,0]
	v_cvt_pk_bf16_f32 v17, v8, v9
	s_waitcnt lgkmcnt(2)
	v_lshlrev_b32_e32 v8, 16, v10
	v_and_b32_e32 v9, 0xffff0000, v10
	v_lshlrev_b32_e32 v10, 16, v11
	v_and_b32_e32 v11, 0xffff0000, v11
	v_pk_fma_f32 v[6:7], v[34:35], v[6:7], v[48:49]
	v_pk_fma_f32 v[2:3], v[36:37], v[2:3], v[50:51]
	v_pk_fma_f32 v[6:7], v[14:15], v[8:9], v[6:7] op_sel_hi:[0,1,1]
	v_pk_fma_f32 v[2:3], v[14:15], v[10:11], v[2:3] op_sel_hi:[0,1,1]
	v_pk_mul_f32 v[6:7], v[70:71], v[6:7]
	v_pk_mul_f32 v[2:3], v[72:73], v[2:3]
	v_cvt_pk_bf16_f32 v6, v6, v7
	v_cvt_pk_bf16_f32 v7, v2, v3
	v_pk_mul_f32 v[4:5], v[4:5], v[106:107] op_sel_hi:[1,0]
	ds_write_b64 v111, v[6:7] offset:17408
	s_waitcnt lgkmcnt(2)
	v_lshlrev_b32_e32 v2, 16, v20
	v_and_b32_e32 v3, 0xffff0000, v20
	v_pk_fma_f32 v[4:5], v[114:115], v[4:5], v[118:119]
	v_pk_mul_f32 v[6:7], v[64:65], v[106:107] op_sel_hi:[1,0]
	v_pk_fma_f32 v[2:3], v[14:15], v[2:3], v[4:5] op_sel_hi:[0,1,1]
	v_lshlrev_b32_e32 v4, 16, v21
	v_and_b32_e32 v5, 0xffff0000, v21
	v_pk_fma_f32 v[6:7], v[116:117], v[6:7], v[120:121]
	v_pk_mul_f32 v[2:3], v[74:75], v[2:3]
	v_pk_fma_f32 v[4:5], v[14:15], v[4:5], v[6:7] op_sel_hi:[0,1,1]
	v_pk_mul_f32 v[4:5], v[76:77], v[4:5]
	v_cvt_pk_bf16_f32 v2, v2, v3
	v_cvt_pk_bf16_f32 v3, v4, v5
	v_pk_mul_f32 v[4:5], v[42:43], v[106:107] op_sel_hi:[1,0]
	v_pk_mul_f32 v[18:19], v[18:19], v[106:107] op_sel_hi:[1,0]
	ds_write_b64 v126, v[2:3] offset:17408
	s_waitcnt lgkmcnt(2)
	v_lshlrev_b32_e32 v2, 16, v22
	v_and_b32_e32 v3, 0xffff0000, v22
	v_pk_fma_f32 v[4:5], v[122:123], v[4:5], v[150:151]
	v_pk_mul_f32 v[6:7], v[12:13], v[106:107] op_sel_hi:[1,0]
	v_pk_fma_f32 v[18:19], v[38:39], v[18:19], v[56:57]
	v_pk_fma_f32 v[2:3], v[14:15], v[2:3], v[4:5] op_sel_hi:[0,1,1]
	v_lshlrev_b32_e32 v4, 16, v23
	v_and_b32_e32 v5, 0xffff0000, v23
	v_pk_fma_f32 v[6:7], v[124:125], v[6:7], v[152:153]
	v_pk_fma_f32 v[18:19], v[14:15], v[24:25], v[18:19] op_sel_hi:[0,1,1]
	v_pk_fma_f32 v[4:5], v[14:15], v[4:5], v[6:7] op_sel_hi:[0,1,1]
	v_pk_mul_f32 v[18:19], v[66:67], v[18:19]
	v_pk_mul_f32 v[2:3], v[78:79], v[2:3]
	v_pk_mul_f32 v[4:5], v[80:81], v[4:5]
	v_cvt_pk_bf16_f32 v16, v18, v19
	v_cvt_pk_bf16_f32 v2, v2, v3
	v_cvt_pk_bf16_f32 v3, v4, v5
	ds_write_b64 v110, v[16:17] offset:17408
	ds_write_b64 v15, v[2:3] offset:17408
	v_mov_b32_e32 v4, v1
	s_waitcnt lgkmcnt(0)
	s_barrier
	v_mov_b32_e32 v13, v0
	v_add_u32_e32 v2, s84, v4
	v_ashrrev_i32_e32 v5, 3, v2
	v_add_u32_e32 v2, s0, v5
	v_ashrrev_i32_e32 v3, 31, v2
	v_lshlrev_b64 v[2:3], 11, v[2:3]
	v_lshl_add_u64 v[2:3], s[72:73], 0, v[2:3]
	s_mov_b64 s[0:1], 0x1c00400
	v_lshl_add_u64 v[10:11], v[2:3], 0, s[0:1]
	v_mul_lo_u32 v2, v5, s3
	v_add_u32_e32 v18, 0, v2
	v_lshlrev_b32_e32 v2, 4, v4
	v_and_b32_e32 v12, 0x70, v2
	v_add_u32_e32 v2, v18, v12
	v_or_b32_e32 v14, 0x80, v12
	ds_read_b128 v[2:5], v2 offset:17408
	v_add_u32_e32 v6, v18, v14
	ds_read_b128 v[6:9], v6 offset:17408
	v_lshl_add_u64 v[16:17], v[10:11], 0, v[12:13]
	v_mov_b32_e32 v15, v0
	s_waitcnt lgkmcnt(1)
	global_store_dwordx4 v[16:17], v[2:5], off
	v_or_b32_e32 v16, 0x180, v12
	v_mov_b32_e32 v17, v0
	v_lshl_add_u64 v[2:3], v[10:11], 0, v[14:15]
	v_or_b32_e32 v14, 0x100, v12
	s_waitcnt lgkmcnt(0)
	global_store_dwordx4 v[2:3], v[6:9], off
	v_add_u32_e32 v2, v18, v14
	ds_read_b128 v[2:5], v2 offset:17408
	v_add_u32_e32 v6, v18, v16
	ds_read_b128 v[6:9], v6 offset:17408
	v_lshl_add_u64 v[14:15], v[10:11], 0, v[14:15]
	s_waitcnt lgkmcnt(1)
	global_store_dwordx4 v[14:15], v[2:5], off
	v_or_b32_e32 v14, 0x200, v12
	s_nop 0
	v_lshl_add_u64 v[2:3], v[10:11], 0, v[16:17]
	s_waitcnt lgkmcnt(0)
	global_store_dwordx4 v[2:3], v[6:9], off
	v_add_u32_e32 v2, v18, v14
	v_or_b32_e32 v16, 0x280, v12
	ds_read_b128 v[2:5], v2 offset:17408
	v_add_u32_e32 v6, v18, v16
	ds_read_b128 v[6:9], v6 offset:17408
	v_mov_b32_e32 v15, v0
	v_lshl_add_u64 v[14:15], v[10:11], 0, v[14:15]
	s_waitcnt lgkmcnt(1)
	global_store_dwordx4 v[14:15], v[2:5], off
	v_or_b32_e32 v14, 0x300, v12
	v_or_b32_e32 v12, 0x380, v12
	v_lshl_add_u64 v[2:3], v[10:11], 0, v[16:17]
	s_waitcnt lgkmcnt(0)
	global_store_dwordx4 v[2:3], v[6:9], off
	v_add_u32_e32 v2, v18, v14
	ds_read_b128 v[2:5], v2 offset:17408
	v_add_u32_e32 v6, v18, v12
	ds_read_b128 v[6:9], v6 offset:17408
	v_mov_b32_e32 v15, v0
	v_lshl_add_u64 v[14:15], v[10:11], 0, v[14:15]
	s_waitcnt lgkmcnt(1)
	global_store_dwordx4 v[14:15], v[2:5], off
	s_nop 1
	v_lshl_add_u64 v[2:3], v[10:11], 0, v[12:13]
	s_waitcnt lgkmcnt(0)
	global_store_dwordx4 v[2:3], v[6:9], off
	s_waitcnt lgkmcnt(0)
	s_barrier
	s_cbranch_scc1 .LBB0_474

.LBB0_472:
	s_lshl_b64 s[28:29], s[38:39], 15
	s_waitcnt lgkmcnt(0)
	s_add_u32 s3, s36, s28
	v_ashrrev_i32_e32 v152, 5, v150
	s_addc_u32 s37, s37, s29
	s_lshl_b64 s[28:29], s[30:31], 13
	v_and_b32_e32 v151, 31, v150
	v_lshlrev_b32_e32 v153, 4, v152
	s_add_u32 s38, s68, s28
	s_addc_u32 s39, s69, s29
	v_lshl_add_u32 v130, v151, 5, v153
	s_add_u32 s28, s3, 0x6000
	v_add_u32_e32 v2, 0xc00, v130
	s_addc_u32 s29, s37, 0
	v_ashrrev_i32_e32 v3, 31, v2
	v_lshl_add_u64 v[6:7], v[2:3], 1, s[28:29]
	global_load_dwordx4 v[2:5], v[6:7], off offset:16 nt
	s_nop 0
	global_load_dwordx4 v[6:9], v[6:7], off nt
	v_ashrrev_i32_e32 v131, 31, v130
	v_lshlrev_b64 v[132:133], 1, v[130:131]
	v_lshl_add_u64 v[54:55], s[28:29], 0, v[132:133]
	v_add_u32_e32 v18, 0x400, v130
	v_ashrrev_i32_e32 v19, 31, v18
	v_lshl_add_u64 v[22:23], v[18:19], 1, s[28:29]
	v_add_u32_e32 v34, 0x800, v130
	v_ashrrev_i32_e32 v35, 31, v34
	v_lshl_add_u64 v[38:39], v[34:35], 1, s[28:29]
	global_load_dwordx4 v[18:21], v[22:23], off offset:16 nt
	s_nop 0
	global_load_dwordx4 v[22:25], v[22:23], off nt
	s_nop 0
	global_load_dwordx4 v[34:37], v[38:39], off offset:16 nt
	s_nop 0
	global_load_dwordx4 v[38:41], v[38:39], off nt
	s_nop 0
	global_load_dwordx4 v[50:53], v[54:55], off offset:16 nt
	s_nop 0
	global_load_dwordx4 v[54:57], v[54:55], off nt
	v_lshlrev_b32_e32 v134, 3, v150
	s_add_u32 s36, s3, 0x2000
	v_lshl_add_u64 v[94:95], s[38:39], 0, v[132:133]
	v_add_u32_e32 v136, 0x200, v134
	v_add_u32_e32 v138, 0x400, v134
	v_add_u32_e32 v140, 0x600, v134
	s_movk_i32 s3, 0x1000
	v_add_u32_e32 v142, 0x800, v134
	s_addc_u32 s37, s37, 0
	v_ashrrev_i32_e32 v135, 31, v134
	v_ashrrev_i32_e32 v137, 31, v136
	v_ashrrev_i32_e32 v139, 31, v138
	v_ashrrev_i32_e32 v141, 31, v140
	v_add_co_u32_e32 v106, vcc, s3, v94
	v_ashrrev_i32_e32 v143, 31, v142
	v_add_u32_e32 v144, 0xa00, v134
	v_lshl_add_u64 v[74:75], v[134:135], 1, s[36:37]
	v_lshl_add_u64 v[78:79], v[136:137], 1, s[36:37]
	v_lshl_add_u64 v[90:91], v[138:139], 1, s[36:37]
	v_lshl_add_u64 v[96:97], v[140:141], 1, s[36:37]
	v_addc_co_u32_e32 v107, vcc, 0, v95, vcc
	v_lshl_add_u64 v[108:109], v[142:143], 1, s[36:37]
	v_ashrrev_i32_e32 v145, 31, v144
	v_add_u32_e32 v146, 0xc00, v134
	v_add_u32_e32 v148, 0xe00, v134
	v_ashrrev_i32_e32 v147, 31, v146
	v_ashrrev_i32_e32 v149, 31, v148
	v_lshl_add_u64 v[122:123], v[146:147], 1, s[36:37]
	v_lshl_add_u64 v[126:127], v[148:149], 1, s[36:37]
	global_load_dwordx4 v[70:73], v[94:95], off nt
	global_load_dwordx4 v[66:69], v[94:95], off offset:2048 nt
	s_nop 0
	global_load_dwordx4 v[74:77], v[74:75], off nt
	s_nop 0
	global_load_dwordx4 v[86:89], v[78:79], off nt
	global_load_dwordx4 v[82:85], v[94:95], off offset:16 nt
	s_nop 0
	global_load_dwordx4 v[78:81], v[94:95], off offset:2064 nt
	global_load_dwordx4 v[102:105], v[96:97], off nt
	s_nop 0
	global_load_dwordx4 v[90:93], v[90:91], off nt
	s_nop 0
	global_load_dwordx4 v[98:101], v[106:107], off nt
	global_load_dwordx4 v[94:97], v[106:107], off offset:2048 nt
	global_load_dwordx4 v[110:113], v[108:109], off nt
	v_lshl_add_u64 v[108:109], v[144:145], 1, s[36:37]
	global_load_dwordx4 v[118:121], v[108:109], off nt
	global_load_dwordx4 v[114:117], v[106:107], off offset:16 nt
	s_nop 0
	global_load_dwordx4 v[106:109], v[106:107], off offset:2064 nt
	s_nop 0
	global_load_dwordx4 v[122:125], v[122:123], off nt
	s_nop 0
	global_load_dwordx4 v[126:129], v[126:127], off nt
	s_xor_b32 s30, s30, 0x7f
	s_ashr_i32 s31, s30, 31
	s_cmpk_lt_i32 s30, 0x800
	s_mov_b64 s[38:39], s[30:31]
	s_mov_b64 s[36:37], s[26:27]
	s_cbranch_scc1 .Lfin_d1_ws
	v_readlane_b32 s28, v254, 59
	v_readlane_b32 s29, v254, 60
	s_nop 3
	s_load_dwordx2 s[36:37], s[28:29], 0xa8
	s_add_i32 s50, s30, 0xfffff800
	s_mov_b64 s[38:39], s[50:51]
.Lfin_d1_ws:
	s_mov_b64 s[28:29], 0x1800
	v_lshl_add_u64 v[180:181], v[132:133], 0, s[28:29]
	s_lshl_b64 s[28:29], s[38:39], 15
	s_waitcnt lgkmcnt(0)
	s_add_u32 s3, s36, s28
	s_addc_u32 s29, s37, s29
	s_add_u32 s28, s3, 0x2000
	s_addc_u32 s29, s29, 0
	s_lshl_b64 s[30:31], s[30:31], 13
	s_add_u32 s30, s68, s30
	s_addc_u32 s31, s69, s31
	s_add_u32 s36, s30, 16
	v_lshl_add_u64 v[178:179], v[132:133], 0, s[52:53]
	s_addc_u32 s37, s31, 0
	v_lshl_add_u64 v[154:155], v[148:149], 1, s[28:29]
	v_lshl_add_u64 v[158:159], v[146:147], 1, s[28:29]
	v_lshl_add_u64 v[244:245], s[36:37], 0, v[180:181]
	v_lshl_add_u64 v[166:167], s[36:37], 0, v[178:179]
	v_lshl_add_u64 v[170:171], v[144:145], 1, s[28:29]
	v_lshl_add_u64 v[174:175], v[142:143], 1, s[28:29]
	v_lshl_add_u64 v[180:181], s[30:31], 0, v[180:181]
	v_lshl_add_u64 v[182:183], s[30:31], 0, v[178:179]
	v_lshl_add_u64 v[186:187], v[140:141], 1, s[28:29]
	v_lshl_add_u64 v[190:191], v[138:139], 1, s[28:29]
	v_lshl_add_u64 v[216:217], v[130:131], 1, s[30:31]
	v_lshl_add_u64 v[196:197], v[136:137], 1, s[28:29]
	v_lshl_add_u64 v[200:201], v[134:135], 1, s[28:29]
	global_load_dwordx4 v[154:157], v[154:155], off
	s_nop 0
	global_load_dwordx4 v[158:161], v[158:159], off
	s_nop 0
	global_load_dwordx4 v[244:247], v[244:245], off
	s_nop 0
	global_load_dwordx4 v[166:169], v[166:167], off
	s_nop 0
	global_load_dwordx4 v[170:173], v[170:171], off
	s_nop 0
	global_load_dwordx4 v[174:177], v[174:175], off
	s_nop 0
	global_load_dwordx4 v[178:181], v[180:181], off
	s_nop 0
	global_load_dwordx4 v[182:185], v[182:183], off
	s_nop 0
	global_load_dwordx4 v[186:189], v[186:187], off
	s_nop 0
	global_load_dwordx4 v[190:193], v[190:191], off
	s_nop 0
	global_load_dwordx4 v[196:199], v[196:197], off
	s_nop 0
	global_load_dwordx4 v[200:203], v[200:201], off
	s_nop 0
	global_load_dwordx4 v[204:207], v[216:217], off offset:2064
	global_load_dwordx4 v[208:211], v[216:217], off offset:2048
	global_load_dwordx4 v[212:215], v[216:217], off offset:16
	s_nop 0
	global_load_dwordx4 v[216:219], v[216:217], off
	s_waitcnt vmcnt(39)
	v_cvt_f32_f16_e32 v10, v2
	s_waitcnt vmcnt(38)
	v_cvt_f32_f16_e32 v228, v6
	v_cvt_f32_f16_sdwa v229, v6 dst_sel:DWORD dst_unused:UNUSED_PAD src0_sel:WORD_1
	v_cvt_f32_f16_sdwa v11, v2 dst_sel:DWORD dst_unused:UNUSED_PAD src0_sel:WORD_1
	v_cvt_f32_f16_e32 v2, v3
	v_cvt_f32_f16_sdwa v3, v3 dst_sel:DWORD dst_unused:UNUSED_PAD src0_sel:WORD_1
	v_cvt_f32_f16_e32 v12, v4
	v_cvt_f32_f16_sdwa v13, v4 dst_sel:DWORD dst_unused:UNUSED_PAD src0_sel:WORD_1
	v_cvt_f32_f16_e32 v230, v7
	v_cvt_f32_f16_sdwa v231, v7 dst_sel:DWORD dst_unused:UNUSED_PAD src0_sel:WORD_1
	v_cvt_f32_f16_e32 v4, v5
	v_cvt_f32_f16_sdwa v5, v5 dst_sel:DWORD dst_unused:UNUSED_PAD src0_sel:WORD_1
	v_pk_add_f32 v[14:15], v[12:13], 0 op_sel_hi:[1,0]
	v_pk_add_f32 v[12:13], v[2:3], 0 op_sel_hi:[1,0]
	v_pk_add_f32 v[2:3], v[228:229], 0 op_sel_hi:[1,0]
	v_pk_add_f32 v[16:17], v[4:5], 0 op_sel_hi:[1,0]
	v_pk_add_f32 v[4:5], v[230:231], 0 op_sel_hi:[1,0]
	v_cvt_f32_f16_e32 v6, v8
	v_cvt_f32_f16_sdwa v7, v8 dst_sel:DWORD dst_unused:UNUSED_PAD src0_sel:WORD_1
	v_cvt_f32_f16_e32 v8, v9
	v_cvt_f32_f16_sdwa v9, v9 dst_sel:DWORD dst_unused:UNUSED_PAD src0_sel:WORD_1
	v_pk_add_f32 v[10:11], v[10:11], 0 op_sel_hi:[1,0]
	v_pk_add_f32 v[6:7], v[6:7], 0 op_sel_hi:[1,0]
	v_pk_add_f32 v[8:9], v[8:9], 0 op_sel_hi:[1,0]
	s_waitcnt vmcnt(37)
	v_cvt_f32_f16_e32 v26, v18
	s_waitcnt vmcnt(36)
	v_cvt_f32_f16_e32 v232, v22
	v_cvt_f32_f16_sdwa v233, v22 dst_sel:DWORD dst_unused:UNUSED_PAD src0_sel:WORD_1
	v_cvt_f32_f16_sdwa v27, v18 dst_sel:DWORD dst_unused:UNUSED_PAD src0_sel:WORD_1
	v_cvt_f32_f16_e32 v18, v19
	v_cvt_f32_f16_sdwa v19, v19 dst_sel:DWORD dst_unused:UNUSED_PAD src0_sel:WORD_1
	v_cvt_f32_f16_e32 v28, v20
	v_cvt_f32_f16_sdwa v29, v20 dst_sel:DWORD dst_unused:UNUSED_PAD src0_sel:WORD_1
	v_cvt_f32_f16_e32 v234, v23
	v_cvt_f32_f16_sdwa v235, v23 dst_sel:DWORD dst_unused:UNUSED_PAD src0_sel:WORD_1
	v_cvt_f32_f16_e32 v20, v21
	v_cvt_f32_f16_sdwa v21, v21 dst_sel:DWORD dst_unused:UNUSED_PAD src0_sel:WORD_1
	v_pk_add_f32 v[30:31], v[28:29], 0 op_sel_hi:[1,0]
	v_pk_add_f32 v[28:29], v[18:19], 0 op_sel_hi:[1,0]
	v_pk_add_f32 v[18:19], v[232:233], 0 op_sel_hi:[1,0]
	v_pk_add_f32 v[32:33], v[20:21], 0 op_sel_hi:[1,0]
	v_pk_add_f32 v[20:21], v[234:235], 0 op_sel_hi:[1,0]
	v_cvt_f32_f16_e32 v22, v24
	v_cvt_f32_f16_sdwa v23, v24 dst_sel:DWORD dst_unused:UNUSED_PAD src0_sel:WORD_1
	v_cvt_f32_f16_e32 v24, v25
	v_cvt_f32_f16_sdwa v25, v25 dst_sel:DWORD dst_unused:UNUSED_PAD src0_sel:WORD_1
	v_pk_add_f32 v[26:27], v[26:27], 0 op_sel_hi:[1,0]
	v_pk_add_f32 v[22:23], v[22:23], 0 op_sel_hi:[1,0]
	v_pk_add_f32 v[24:25], v[24:25], 0 op_sel_hi:[1,0]
	s_waitcnt vmcnt(35)
	v_cvt_f32_f16_e32 v42, v34
	s_waitcnt vmcnt(34)
	v_cvt_f32_f16_e32 v236, v38
	v_cvt_f32_f16_sdwa v237, v38 dst_sel:DWORD dst_unused:UNUSED_PAD src0_sel:WORD_1
	v_cvt_f32_f16_e32 v238, v39
	v_cvt_f32_f16_sdwa v239, v39 dst_sel:DWORD dst_unused:UNUSED_PAD src0_sel:WORD_1
	v_cvt_f32_f16_sdwa v43, v34 dst_sel:DWORD dst_unused:UNUSED_PAD src0_sel:WORD_1
	v_cvt_f32_f16_e32 v34, v35
	v_cvt_f32_f16_sdwa v35, v35 dst_sel:DWORD dst_unused:UNUSED_PAD src0_sel:WORD_1
	v_cvt_f32_f16_e32 v44, v36
	v_cvt_f32_f16_sdwa v45, v36 dst_sel:DWORD dst_unused:UNUSED_PAD src0_sel:WORD_1
	v_cvt_f32_f16_e32 v36, v37
	v_cvt_f32_f16_sdwa v37, v37 dst_sel:DWORD dst_unused:UNUSED_PAD src0_sel:WORD_1
	v_cvt_f32_f16_e32 v38, v40
	v_pk_add_f32 v[46:47], v[44:45], 0 op_sel_hi:[1,0]
	v_pk_add_f32 v[44:45], v[34:35], 0 op_sel_hi:[1,0]
	v_pk_add_f32 v[48:49], v[36:37], 0 op_sel_hi:[1,0]
	v_pk_add_f32 v[36:37], v[238:239], 0 op_sel_hi:[1,0]
	v_pk_add_f32 v[34:35], v[236:237], 0 op_sel_hi:[1,0]
	v_cvt_f32_f16_sdwa v39, v40 dst_sel:DWORD dst_unused:UNUSED_PAD src0_sel:WORD_1
	v_cvt_f32_f16_e32 v40, v41
	v_cvt_f32_f16_sdwa v41, v41 dst_sel:DWORD dst_unused:UNUSED_PAD src0_sel:WORD_1
	v_pk_add_f32 v[42:43], v[42:43], 0 op_sel_hi:[1,0]
	v_pk_add_f32 v[38:39], v[38:39], 0 op_sel_hi:[1,0]
	v_pk_add_f32 v[40:41], v[40:41], 0 op_sel_hi:[1,0]
	s_waitcnt vmcnt(33)
	v_cvt_f32_f16_e32 v58, v50
	s_waitcnt vmcnt(32)
	v_cvt_f32_f16_e32 v240, v54
	v_cvt_f32_f16_sdwa v241, v54 dst_sel:DWORD dst_unused:UNUSED_PAD src0_sel:WORD_1
	v_cvt_f32_f16_e32 v242, v55
	v_cvt_f32_f16_sdwa v243, v55 dst_sel:DWORD dst_unused:UNUSED_PAD src0_sel:WORD_1
	v_cvt_f32_f16_sdwa v59, v50 dst_sel:DWORD dst_unused:UNUSED_PAD src0_sel:WORD_1
	v_cvt_f32_f16_e32 v50, v51
	v_cvt_f32_f16_sdwa v51, v51 dst_sel:DWORD dst_unused:UNUSED_PAD src0_sel:WORD_1
	v_cvt_f32_f16_e32 v60, v52
	v_cvt_f32_f16_sdwa v61, v52 dst_sel:DWORD dst_unused:UNUSED_PAD src0_sel:WORD_1
	v_cvt_f32_f16_e32 v52, v53
	v_cvt_f32_f16_sdwa v53, v53 dst_sel:DWORD dst_unused:UNUSED_PAD src0_sel:WORD_1
	v_cvt_f32_f16_e32 v54, v56
	v_pk_add_f32 v[62:63], v[60:61], 0 op_sel_hi:[1,0]
	v_pk_add_f32 v[60:61], v[50:51], 0 op_sel_hi:[1,0]
	v_pk_add_f32 v[64:65], v[52:53], 0 op_sel_hi:[1,0]
	v_pk_add_f32 v[52:53], v[242:243], 0 op_sel_hi:[1,0]
	v_pk_add_f32 v[50:51], v[240:241], 0 op_sel_hi:[1,0]
	v_cvt_f32_f16_sdwa v55, v56 dst_sel:DWORD dst_unused:UNUSED_PAD src0_sel:WORD_1
	v_cvt_f32_f16_e32 v56, v57
	v_cvt_f32_f16_sdwa v57, v57 dst_sel:DWORD dst_unused:UNUSED_PAD src0_sel:WORD_1
	v_pk_add_f32 v[58:59], v[58:59], 0 op_sel_hi:[1,0]
	v_pk_add_f32 v[56:57], v[56:57], 0 op_sel_hi:[1,0]
	v_pk_add_f32 v[54:55], v[54:55], 0 op_sel_hi:[1,0]
	s_waitcnt vmcnt(29)
	s_nop 0
	v_mfma_f32_32x32x16_f16 v[50:65], v[70:73], v[74:77], v[50:65]
	v_mfma_f32_32x32x16_f16 v[34:49], v[66:69], v[74:77], v[34:49]
	s_waitcnt vmcnt(28)
	v_mfma_f32_32x32x16_f16 v[18:33], v[70:73], v[86:89], v[18:33]
	v_mfma_f32_32x32x16_f16 v[2:17], v[66:69], v[86:89], v[2:17]
	s_waitcnt vmcnt(24)
	v_mfma_f32_32x32x16_f16 v[50:65], v[82:85], v[90:93], v[50:65]
	v_mfma_f32_32x32x16_f16 v[34:49], v[78:81], v[90:93], v[34:49]
	v_mfma_f32_32x32x16_f16 v[18:33], v[82:85], v[102:105], v[18:33]
	v_mfma_f32_32x32x16_f16 v[2:17], v[78:81], v[102:105], v[2:17]
	s_waitcnt vmcnt(21)
	v_mfma_f32_32x32x16_f16 v[50:65], v[98:101], v[110:113], v[50:65]
	v_mfma_f32_32x32x16_f16 v[34:49], v[94:97], v[110:113], v[34:49]
	s_waitcnt vmcnt(20)
	v_mfma_f32_32x32x16_f16 v[18:33], v[98:101], v[118:121], v[18:33]
	v_mfma_f32_32x32x16_f16 v[2:17], v[94:97], v[118:121], v[2:17]
	s_waitcnt vmcnt(17)
	v_mfma_f32_32x32x16_f16 v[50:65], v[114:117], v[122:125], v[50:65]
	v_mfma_f32_32x32x16_f16 v[34:49], v[106:109], v[122:125], v[34:49]
	s_waitcnt vmcnt(16)
	v_mfma_f32_32x32x16_f16 v[18:33], v[114:117], v[126:129], v[18:33]
	v_mfma_f32_32x32x16_f16 v[2:17], v[106:109], v[126:129], v[2:17]
	s_branch .LBB0_451
